# same schedule as v88 (pre-P1 seam 512 items, P1 idle slot 2048 items), pre-P1 range now selected at run time so a grid other than 256 workgroups keeps the original ranges
# baseline (speedup 1.0000x reference)
; __global__ void __launch_bounds__(512, 2) mk_fwd(Args args) {
;     ...
;     if (IN(0) && IN(1)) { if (DEPTH == 2) { xcd_barrier_arrive(xbar); CONVERT_ITEMS(I_L, I_L + 1280); xcd_barrier_wait(xbar); } else xcd_barrier(xbar); }
.LBB0_160:
	s_or_b64 exec, exec, s[0:1]
	v_mov_b32_e32 v0, v252
	s_lshl_b32 s14, s96, 3
	v_readfirstlane_b32 s0, v0
	s_ashr_i32 s2, s0, 6
	s_add_i32 s3, s14, s2
	s_lshl_b32 s0, s86, 3
	s_add_i32 s15, s3, 0x1780
	v_writelane_b32 v253, s0, 34
	s_mov_b64 s[0:1], s[20:21]
	s_movk_i32 s100, 0x1c7f
	s_cmpk_eq_i32 s86, 0x100
	s_cselect_b32 s100, 0x197f, s100
	s_cmp_gt_i32 s15, s100
	s_cbranch_scc1 .LBB0_209
	s_add_u32 s24, s0, 0x200000
	s_addc_u32 s25, s1, 0
	s_add_u32 s26, s0, 0x3e00000
	s_addc_u32 s27, s1, 0
	s_add_u32 s28, s0, 0x4e00000
	s_addc_u32 s29, s1, 0
	s_add_u32 s30, s0, 0x5e00000
	s_addc_u32 s31, s1, 0
	s_add_u32 s34, s0, 0x10000
	s_addc_u32 s35, s1, 0
	v_and_b32_e32 v2, 63, v0
	v_bfe_u32 v80, v0, 4, 2
	v_bfe_u32 v82, v0, 3, 3
	v_lshlrev_b32_e32 v0, 3, v0
	s_add_u32 s37, s0, 0x14000
	s_mulk_i32 s2, 0x4100
	v_lshlrev_b32_e32 v68, 2, v2
	v_and_b32_e32 v0, 56, v0
	s_addc_u32 s38, s1, 0
	s_add_i32 s2, s2, 0
	v_and_b32_e32 v4, 60, v68
	v_mul_u32_u24_e32 v3, 0x104, v0
	v_lshlrev_b32_e32 v5, 2, v82
	v_readlane_b32 s40, v253, 18
	v_lshl_add_u32 v1, v4, 2, s2
	s_movk_i32 s0, 0x104
	v_add3_u32 v83, s2, v3, v5
	v_readlane_b32 s50, v253, 28
	v_readlane_b32 s51, v253, 29
	v_or_b32_e32 v3, 4, v80
	v_mov_b32_e32 v69, 0
	v_mad_u32_u24 v81, v80, s0, v1
	v_readlane_b32 s41, v253, 19
	v_readlane_b32 s42, v253, 20
	v_readlane_b32 s43, v253, 21
	v_readlane_b32 s44, v253, 22
	v_readlane_b32 s45, v253, 23
	v_readlane_b32 s46, v253, 24
	v_readlane_b32 s47, v253, 25
	v_readlane_b32 s48, v253, 26
	v_readlane_b32 s49, v253, 27
	v_readlane_b32 s52, v253, 30
	v_readlane_b32 s53, v253, 31
	v_readlane_b32 s54, v253, 32
	v_readlane_b32 s55, v253, 33
	s_cmp_lg_u64 s[50:51], 0
	v_mul_u32_u24_e32 v3, 0x104, v3
	v_or_b32_e32 v84, 8, v82
	v_or_b32_e32 v85, 16, v82
	v_or_b32_e32 v86, 24, v82
	v_or_b32_e32 v87, 32, v82
	v_or_b32_e32 v88, 40, v82
	v_or_b32_e32 v89, 48, v82
	v_or_b32_e32 v90, 56, v82
	s_cselect_b64 s[0:1], -1, 0
	v_add_u32_e32 v91, s2, v68
	v_lshl_add_u64 v[70:71], s[16:17], 0, v[68:69]
	s_mov_b32 s39, 0x8000
	s_mov_b32 s40, 0x10000
	s_mov_b32 s41, 0x18000
	s_mov_b32 s42, 0x20000
	s_mov_b32 s43, 0x28000
	s_mov_b32 s44, 0x30000
	s_mov_b32 s45, 0x38000
	s_mov_b32 s46, 0x40000
	s_mov_b32 s47, 0x48000
	s_mov_b32 s48, 0x50000
	s_mov_b32 s49, 0x58000
	s_mov_b32 s50, 0x60000
	s_mov_b32 s51, 0x68000
	s_mov_b32 s52, 0x70000
	s_mov_b32 s53, 0x78000
	v_add_u32_e32 v92, 0x410, v81
	v_add_u32_e32 v93, 0x418, v81
	v_add_u32_e32 v94, 0x820, v81
	v_add_u32_e32 v95, 0x828, v81
	v_add_u32_e32 v96, 0xc30, v81
	v_add_u32_e32 v97, 0xc38, v81
	v_add_u32_e32 v98, 0x1040, v81
	v_add_u32_e32 v99, 0x1048, v81
	v_add_u32_e32 v100, 0x1450, v81
	v_add_u32_e32 v101, 0x1458, v81
	v_add_u32_e32 v102, 0x1860, v81
	v_add_u32_e32 v103, 0x1868, v81
	v_add_u32_e32 v104, 0x1c70, v81
	v_add_u32_e32 v105, 0x1c78, v81
	v_add_u32_e32 v106, 0x2080, v81
	v_add_u32_e32 v107, 0x2088, v81
	v_add_u32_e32 v108, 0x2490, v81
	v_add_u32_e32 v109, 0x2498, v81
	v_add_u32_e32 v110, 0x28a0, v81
	v_add_u32_e32 v111, 0x28a8, v81
	v_add_u32_e32 v112, 0x2cb0, v81
	v_add_u32_e32 v113, 0x2cb8, v81
	v_add_u32_e32 v114, 0x30c0, v81
	v_add_u32_e32 v115, 0x30c8, v81
	v_add_u32_e32 v116, 0x34d0, v81
	v_add_u32_e32 v117, 0x34d8, v81
	v_add_u32_e32 v118, 0x38e0, v81
	v_add_u32_e32 v119, 0x38e8, v81
	v_add_u32_e32 v120, 0x3cf0, v81
	v_lshlrev_b32_e32 v72, 2, v2
	s_mov_b32 s54, 0xf0000
	s_mov_b32 s55, 0x10e000
	s_mov_b32 s56, 0x12c000
	s_mov_b32 s57, 0x14a000
	s_mov_b32 s58, 0x168000
	s_mov_b32 s59, 0x186000
	s_mov_b32 s60, 0x1a4000
	s_mov_b32 s61, 0x1c2000
	v_lshlrev_b32_e32 v68, 2, v4
	v_add_u32_e32 v121, 0x3cf8, v81
	v_lshlrev_b32_e32 v74, 1, v0
	v_add_u32_e32 v122, v1, v3
	s_branch .LBB0_163
.LBB0_162:
	v_readlane_b32 s2, v253, 34
	s_add_i32 s15, s15, s2
	s_movk_i32 s100, 0x1c7f
	s_cmpk_eq_i32 s86, 0x100
	s_cselect_b32 s100, 0x197f, s100
	s_cmp_gt_i32 s15, s100
	s_cbranch_scc1 .LBB0_209

; __device__ __forceinline__ void p0_transpose_item(const float* W, int K, int N, bf16* WT, float* scr, int item, int lane, const float* scale, const float* cb, float* c1, float* c2) {
;     const int nblk = N / 64, kb = item / nblk, nb = item % nblk, k0 = 64 * kb, n0 = 64 * nb;
;     const int lr = lane >> 4, lc = (lane & 15) * 4;
;     f32x4 v[16];
; #pragma unroll
;     for (int i = 0; i < 16; ++i) v[i] = *(const f32x4*)(W + (size_t)(k0 + 4 * i + lr) * N + n0 + lc);
; #pragma unroll
;     for (int i = 0; i < 16; ++i) { const int kk = 4 * i + lr; f32x4 w = v[i]; if (scale) w = w * scale[k0 + kk]; float* d = scr + kk * 65 + lc; d[0] = w[0]; d[1] = w[1]; d[2] = w[2]; d[3] = w[3]; }
.LBB0_434:
	s_andn2_b64 vcc, exec, s[2:3]
	s_cbranch_vccnz .LBB0_462
	s_lshl_b64 s[6:7], s[0:1], 24
	s_add_u32 s4, s16, s6
	s_addc_u32 s5, s17, s7
	s_lshl_b32 s2, s0, 11
	s_ashr_i32 s3, s2, 31
	v_readlane_b32 s48, v253, 18
	s_lshl_b64 s[2:3], s[2:3], 2
	v_readlane_b32 s58, v253, 28
	v_readlane_b32 s49, v253, 19
	v_readlane_b32 s59, v253, 29
	s_add_u32 s14, s58, s2
	v_readlane_b32 s51, v253, 21
	s_addc_u32 s15, s59, s3
	s_lshl_b32 s49, s47, 1
	s_lshl_b32 s24, s47, 6
	v_readlane_b32 s50, v253, 20
	s_add_i32 s49, s49, 0x1da00
	s_and_b32 s51, s24, 0x7c0
	s_and_b32 s50, s49, 0x1ffc0
	s_lshl_b32 s48, s51, 2
	s_add_u32 s4, s4, s48
	v_or_b32_e32 v64, s50, v69
	s_addc_u32 s5, s5, 0
	v_lshlrev_b32_e32 v168, 2, v68
	v_lshl_add_u64 v[0:1], s[4:5], 0, v[168:169]
	v_lshlrev_b32_e32 v168, 13, v64
	v_lshl_add_u64 v[0:1], v[0:1], 0, v[168:169]
	v_add_co_u32_e32 v2, vcc, s90, v0
	s_mov_b32 s4, 0x20000
	s_nop 0
	v_addc_co_u32_e32 v3, vcc, 0, v1, vcc
	global_load_dwordx4 v[56:59], v[0:1], off
	global_load_dwordx4 v[60:63], v[2:3], off
	v_add_co_u32_e32 v2, vcc, s88, v0
	v_readlane_b32 s24, v254, 34
	s_nop 0
	v_addc_co_u32_e32 v3, vcc, 0, v1, vcc
	v_add_co_u32_e32 v4, vcc, s85, v0
	v_readlane_b32 s25, v254, 35
	s_nop 0
	v_addc_co_u32_e32 v5, vcc, 0, v1, vcc
	global_load_dwordx4 v[48:51], v[2:3], off
	global_load_dwordx4 v[52:55], v[4:5], off
	v_add_co_u32_e32 v2, vcc, s4, v0
	s_mov_b32 s4, 0x28000
	s_nop 0
	v_addc_co_u32_e32 v3, vcc, 0, v1, vcc
	v_add_co_u32_e32 v4, vcc, s4, v0
	s_mov_b32 s4, 0x30000
	s_nop 0
	v_addc_co_u32_e32 v5, vcc, 0, v1, vcc
	global_load_dwordx4 v[40:43], v[2:3], off
	global_load_dwordx4 v[44:47], v[4:5], off
	v_add_co_u32_e32 v2, vcc, s4, v0
	s_mov_b32 s4, 0x38000
	s_nop 0
	v_addc_co_u32_e32 v3, vcc, 0, v1, vcc
	v_add_co_u32_e32 v4, vcc, s4, v0
	s_mov_b32 s4, 0x40000
	s_nop 0
	v_addc_co_u32_e32 v5, vcc, 0, v1, vcc
	global_load_dwordx4 v[32:35], v[2:3], off
	global_load_dwordx4 v[36:39], v[4:5], off
	v_add_co_u32_e32 v2, vcc, s4, v0
	s_mov_b32 s4, 0x48000
	s_nop 0
	v_addc_co_u32_e32 v3, vcc, 0, v1, vcc
	v_add_co_u32_e32 v4, vcc, s4, v0
	s_mov_b32 s4, 0x50000
	s_nop 0
	v_addc_co_u32_e32 v5, vcc, 0, v1, vcc
	global_load_dwordx4 v[24:27], v[2:3], off
	global_load_dwordx4 v[28:31], v[4:5], off
	v_add_co_u32_e32 v2, vcc, s4, v0
	s_mov_b32 s4, 0x58000
	s_nop 0
	v_addc_co_u32_e32 v3, vcc, 0, v1, vcc
	v_add_co_u32_e32 v4, vcc, s4, v0
	s_mov_b32 s4, 0x60000
	s_nop 0
	v_addc_co_u32_e32 v5, vcc, 0, v1, vcc
	global_load_dwordx4 v[16:19], v[2:3], off
	global_load_dwordx4 v[20:23], v[4:5], off
	v_add_co_u32_e32 v2, vcc, s4, v0
	v_cndmask_b32_e64 v65, 0, 1, s[24:25]
	s_nop 0
	v_addc_co_u32_e32 v3, vcc, 0, v1, vcc
	v_add_co_u32_e32 v4, vcc, 0x68000, v0
	v_cmp_ne_u32_e64 s[4:5], 1, v65
	s_nop 0
	v_addc_co_u32_e32 v5, vcc, 0, v1, vcc
	global_load_dwordx4 v[8:11], v[2:3], off
	global_load_dwordx4 v[12:15], v[4:5], off
	v_add_co_u32_e32 v2, vcc, 0x70000, v0
	v_add_lshl_u32 v75, s50, v69, 2
	s_nop 0
	v_addc_co_u32_e32 v3, vcc, 0, v1, vcc
	v_add_co_u32_e32 v4, vcc, 0x78000, v0
	v_readlane_b32 s52, v253, 22
	s_nop 0
	v_addc_co_u32_e32 v5, vcc, 0, v1, vcc
	global_load_dwordx4 v[0:3], v[2:3], off
	s_nop 0
	global_load_dwordx4 v[4:7], v[4:5], off
	s_andn2_b64 vcc, exec, s[24:25]
	v_readlane_b32 s53, v253, 23
	v_readlane_b32 s54, v253, 24
	v_readlane_b32 s55, v253, 25
	v_readlane_b32 s56, v253, 26
	v_readlane_b32 s57, v253, 27
	v_readlane_b32 s60, v253, 30
	v_readlane_b32 s61, v253, 31
	v_readlane_b32 s62, v253, 32
	v_readlane_b32 s63, v253, 33
	s_cbranch_vccnz .LBB0_468
	v_lshlrev_b32_e32 v64, 2, v64
	global_load_dword v64, v64, s[14:15]
	s_nop 0
	global_load_dword v92, v75, s[14:15] offset:16
	global_load_dword v126, v75, s[14:15] offset:32
	global_load_dword v128, v75, s[14:15] offset:48
	global_load_dword v130, v75, s[14:15] offset:64
	global_load_dword v132, v75, s[14:15] offset:80
	global_load_dword v134, v75, s[14:15] offset:96
	global_load_dword v136, v75, s[14:15] offset:112
	global_load_dword v138, v75, s[14:15] offset:128
	global_load_dword v140, v75, s[14:15] offset:144
	global_load_dword v142, v75, s[14:15] offset:160
	global_load_dword v144, v75, s[14:15] offset:176
	global_load_dword v146, v75, s[14:15] offset:192
	global_load_dword v148, v75, s[14:15] offset:208
	global_load_dword v150, v75, s[14:15] offset:224
	global_load_dword v152, v75, s[14:15] offset:240
	s_waitcnt vmcnt(0)
	v_pk_mul_f32 v[76:77], v[58:59], v[64:65] op_sel_hi:[1,0]
	v_pk_mul_f32 v[78:79], v[56:57], v[64:65] op_sel_hi:[1,0]
	v_pk_mul_f32 v[66:67], v[62:63], v[92:93] op_sel_hi:[1,0]
	v_pk_mul_f32 v[64:65], v[60:61], v[92:93] op_sel_hi:[1,0]
	s_cbranch_execnz .LBB0_438

; #define LDS_WAIT() asm volatile("s_waitcnt lgkmcnt(0)" ::: "memory")
; __device__ __forceinline__ unsigned pk2(float lo, float hi) { unsigned r; asm("v_cvt_pk_bf16_f32 %0, %1, %2" : "=v"(r) : "v"(lo), "v"(hi)); return r; }
; __device__ __forceinline__ void p0_transpose_item(const float* W, int K, int N, bf16* WT, float* scr, int item, int lane, const float* scale, const float* cb, float* c1, float* c2) {
;     ...
;     for (int i = 0; i < 16; ++i) { const int kk = 4 * i + lr; f32x4 w = v[i]; if (scale) w = w * scale[k0 + kk]; float* d = scr + kk * 65 + lc; d[0] = w[0]; d[1] = w[1]; d[2] = w[2]; d[3] = w[3]; }
;     LDS_WAIT(); asm volatile("" ::: "memory");
;     const int c = lane & 7;
; #pragma unroll
;     for (int j = 0; j < 8; ++j) { const int n = (lane >> 3) + 8 * j; const float* sp = scr + (8 * c) * 65 + n;
;         v4u o; o.x = pk2(sp[0 * 65], sp[1 * 65]); o.y = pk2(sp[2 * 65], sp[3 * 65]); o.z = pk2(sp[4 * 65], sp[5 * 65]); o.w = pk2(sp[6 * 65], sp[7 * 65]);
;         *(v4u*)(WT + (size_t)(n0 + n) * K + k0 + 8 * c) = o; }
.LBB0_459:
	v_add_u32_e32 v0, 0x34d0, v90
	ds_write2_b32 v0, v14, v15 offset1:1
	v_add_u32_e32 v0, 0x34d8, v90
	ds_write2_b32 v0, v12, v13 offset1:1
	v_add_u32_e32 v0, 0x38e0, v90
	ds_write2_b32 v0, v8, v9 offset1:1
	v_add_u32_e32 v0, 0x38e8, v90
	ds_write2_b32 v0, v10, v11 offset1:1
	s_waitcnt lgkmcnt(0)
	ds_read_b32 v2, v81
	ds_read_b32 v3, v81 offset:260
	s_lshl_b64 s[4:5], s[0:1], 22
	s_waitcnt lgkmcnt(0)
	v_cvt_pk_bf16_f32 v2, v2, v3
	ds_read_b32 v3, v81 offset:520
	ds_read_b32 v4, v81 offset:780
	s_waitcnt lgkmcnt(0)
	v_cvt_pk_bf16_f32 v3, v3, v4
	ds_read_b32 v4, v81 offset:1040
	ds_read_b32 v5, v81 offset:1300
	s_waitcnt lgkmcnt(0)
	v_cvt_pk_bf16_f32 v4, v4, v5
	ds_read_b32 v5, v81 offset:1560
	ds_read_b32 v6, v81 offset:1820
	s_lshl_b64 s[4:5], s[4:5], 1
	s_add_u32 s1, s39, s4
	s_addc_u32 s5, s40, s5
	s_lshl_b32 s4, s50, 1
	s_add_u32 s4, s1, s4
	s_addc_u32 s5, s5, 0
	v_lshlrev_b32_e32 v168, 1, v70
	s_waitcnt lgkmcnt(0)
	v_cvt_pk_bf16_f32 v5, v5, v6
	v_or_b32_e32 v6, s51, v80
	v_lshl_add_u64 v[0:1], s[4:5], 0, v[168:169]
	v_lshlrev_b32_e32 v168, 12, v6
	v_lshl_add_u64 v[6:7], v[0:1], 0, v[168:169]
	global_store_dwordx4 v[6:7], v[2:5], off
	ds_read_b32 v2, v81 offset:32
	ds_read_b32 v3, v81 offset:292
	s_waitcnt lgkmcnt(0)
	v_cvt_pk_bf16_f32 v2, v2, v3
	ds_read_b32 v3, v81 offset:552
	ds_read_b32 v4, v81 offset:812
	s_waitcnt lgkmcnt(0)
	v_cvt_pk_bf16_f32 v3, v3, v4
	ds_read_b32 v4, v81 offset:1072
	ds_read_b32 v5, v81 offset:1332
	s_waitcnt lgkmcnt(0)
	v_cvt_pk_bf16_f32 v4, v4, v5
	ds_read_b32 v5, v81 offset:1592
	ds_read_b32 v6, v81 offset:1852
	s_waitcnt lgkmcnt(0)
	v_cvt_pk_bf16_f32 v5, v5, v6
	v_or_b32_e32 v6, s51, v82
	v_lshlrev_b32_e32 v168, 12, v6
	v_lshl_add_u64 v[6:7], v[0:1], 0, v[168:169]
	global_store_dwordx4 v[6:7], v[2:5], off
	ds_read_b32 v2, v81 offset:64
	ds_read_b32 v3, v81 offset:324
	s_waitcnt lgkmcnt(0)
	v_cvt_pk_bf16_f32 v2, v2, v3
	ds_read_b32 v3, v81 offset:584
	ds_read_b32 v4, v81 offset:844
	s_waitcnt lgkmcnt(0)
	v_cvt_pk_bf16_f32 v3, v3, v4
	ds_read_b32 v4, v81 offset:1104
	ds_read_b32 v5, v81 offset:1364
	s_waitcnt lgkmcnt(0)
	v_cvt_pk_bf16_f32 v4, v4, v5
	ds_read_b32 v5, v81 offset:1624
	ds_read_b32 v6, v81 offset:1884
	s_waitcnt lgkmcnt(0)
	v_cvt_pk_bf16_f32 v5, v5, v6
	v_or_b32_e32 v6, s51, v83
	v_lshlrev_b32_e32 v168, 12, v6
	v_lshl_add_u64 v[6:7], v[0:1], 0, v[168:169]
	global_store_dwordx4 v[6:7], v[2:5], off
	ds_read_b32 v2, v81 offset:96
	ds_read_b32 v3, v81 offset:356
	s_waitcnt lgkmcnt(0)
	v_cvt_pk_bf16_f32 v2, v2, v3
	ds_read_b32 v3, v81 offset:616
	ds_read_b32 v4, v81 offset:876
	s_waitcnt lgkmcnt(0)
	v_cvt_pk_bf16_f32 v3, v3, v4
	ds_read_b32 v4, v81 offset:1136
	ds_read_b32 v5, v81 offset:1396
	s_waitcnt lgkmcnt(0)
	v_cvt_pk_bf16_f32 v4, v4, v5
	ds_read_b32 v5, v81 offset:1656
	ds_read_b32 v6, v81 offset:1916
	s_waitcnt lgkmcnt(0)
	v_cvt_pk_bf16_f32 v5, v5, v6
	v_or_b32_e32 v6, s51, v84
	v_lshlrev_b32_e32 v168, 12, v6
	v_lshl_add_u64 v[6:7], v[0:1], 0, v[168:169]
	global_store_dwordx4 v[6:7], v[2:5], off
	ds_read_b32 v2, v81 offset:128
	ds_read_b32 v3, v81 offset:388
	s_waitcnt lgkmcnt(0)
	v_cvt_pk_bf16_f32 v2, v2, v3
	ds_read_b32 v3, v81 offset:648
	ds_read_b32 v4, v81 offset:908
	s_waitcnt lgkmcnt(0)
	v_cvt_pk_bf16_f32 v3, v3, v4
	ds_read_b32 v4, v81 offset:1168
	ds_read_b32 v5, v81 offset:1428
	s_waitcnt lgkmcnt(0)
	v_cvt_pk_bf16_f32 v4, v4, v5
	ds_read_b32 v5, v81 offset:1688
	ds_read_b32 v6, v81 offset:1948
	s_waitcnt lgkmcnt(0)
	v_cvt_pk_bf16_f32 v5, v5, v6
	v_or_b32_e32 v6, s51, v85
	v_lshlrev_b32_e32 v168, 12, v6
	v_lshl_add_u64 v[6:7], v[0:1], 0, v[168:169]
	global_store_dwordx4 v[6:7], v[2:5], off
	ds_read_b32 v2, v81 offset:160
	ds_read_b32 v3, v81 offset:420
	s_waitcnt lgkmcnt(0)
	v_cvt_pk_bf16_f32 v2, v2, v3
	ds_read_b32 v3, v81 offset:680
	ds_read_b32 v4, v81 offset:940
	s_waitcnt lgkmcnt(0)
	v_cvt_pk_bf16_f32 v3, v3, v4
	ds_read_b32 v4, v81 offset:1200
	ds_read_b32 v5, v81 offset:1460
	s_waitcnt lgkmcnt(0)
	v_cvt_pk_bf16_f32 v4, v4, v5
	ds_read_b32 v5, v81 offset:1720
	ds_read_b32 v6, v81 offset:1980
	s_waitcnt lgkmcnt(0)
	v_cvt_pk_bf16_f32 v5, v5, v6
	v_or_b32_e32 v6, s51, v86
	v_lshlrev_b32_e32 v168, 12, v6
	v_lshl_add_u64 v[6:7], v[0:1], 0, v[168:169]
	global_store_dwordx4 v[6:7], v[2:5], off
	ds_read_b32 v2, v81 offset:192
	ds_read_b32 v3, v81 offset:452
	s_waitcnt lgkmcnt(0)
	v_cvt_pk_bf16_f32 v2, v2, v3
	ds_read_b32 v3, v81 offset:712
	ds_read_b32 v4, v81 offset:972
	s_waitcnt lgkmcnt(0)
	v_cvt_pk_bf16_f32 v3, v3, v4
	ds_read_b32 v4, v81 offset:1232
	ds_read_b32 v5, v81 offset:1492
	s_waitcnt lgkmcnt(0)
	v_cvt_pk_bf16_f32 v4, v4, v5
	ds_read_b32 v5, v81 offset:1752
	ds_read_b32 v6, v81 offset:2012
	s_waitcnt lgkmcnt(0)
	v_cvt_pk_bf16_f32 v5, v5, v6
	v_or_b32_e32 v6, s51, v87
	v_lshlrev_b32_e32 v168, 12, v6
	v_lshl_add_u64 v[6:7], v[0:1], 0, v[168:169]
	global_store_dwordx4 v[6:7], v[2:5], off
	ds_read_b32 v2, v81 offset:224
	ds_read_b32 v3, v81 offset:484
	s_waitcnt lgkmcnt(0)
	v_cvt_pk_bf16_f32 v2, v2, v3
	ds_read_b32 v3, v81 offset:744
	ds_read_b32 v4, v81 offset:1004
	s_waitcnt lgkmcnt(0)
	v_cvt_pk_bf16_f32 v3, v3, v4
	ds_read_b32 v4, v81 offset:1264
	ds_read_b32 v5, v81 offset:1524
	s_waitcnt lgkmcnt(0)
	v_cvt_pk_bf16_f32 v4, v4, v5
	ds_read_b32 v5, v81 offset:1784
	ds_read_b32 v6, v81 offset:2044
	s_lshl_b32 s1, s49, 13
	s_and_b32 s1, s1, 0x3ff80000
	s_add_u32 s1, s6, s1
	s_addc_u32 s5, s7, 0
	s_and_b32 s4, s47, 31
	s_waitcnt lgkmcnt(0)
; __device__ __forceinline__ unsigned pk2(float lo, float hi) { unsigned r; asm("v_cvt_pk_bf16_f32 %0, %1, %2" : "=v"(r) : "v"(lo), "v"(hi)); return r; }
; __device__ __forceinline__ unsigned f2bf(float f) { return pk2(f, 0.f) & 0xffffu; }
; __device__ __forceinline__ void p0_transpose_item(const float* W, int K, int N, bf16* WT, float* scr, int item, int lane, const float* scale, const float* cb, float* c1, float* c2) {
;     ...
;     for (int j = 0; j < 8; ++j) { const int n = (lane >> 3) + 8 * j; const float* sp = scr + (8 * c) * 65 + n;
;         v4u o; o.x = pk2(sp[0 * 65], sp[1 * 65]); o.y = pk2(sp[2 * 65], sp[3 * 65]); o.z = pk2(sp[4 * 65], sp[5 * 65]); o.w = pk2(sp[6 * 65], sp[7 * 65]);
;         *(v4u*)(WT + (size_t)(n0 + n) * K + k0 + 8 * c) = o; }
;     if (c1) { float a1 = 0.f, a2 = 0.f;
;         for (int kk = 0; kk < 64; ++kk) { a1 += __uint_as_float(f2bf(scr[kk * 65 + lane]) << 16); a2 += cb[k0 + kk] * W[(size_t)(k0 + kk) * N + n0 + lane]; }
	v_cvt_pk_bf16_f32 v5, v5, v6
	v_or_b32_e32 v6, s51, v88
	s_lshl_b32 s4, s4, 8
	v_readlane_b32 s52, v253, 18
	v_lshlrev_b32_e32 v168, 12, v6
	s_or_b32 s4, s1, s4
	s_lshl_b32 s1, s50, 2
	v_readlane_b32 s64, v253, 30
	v_lshl_add_u64 v[0:1], v[0:1], 0, v[168:169]
	v_readlane_b32 s65, v253, 31
	s_add_u32 s1, s64, s1
	global_store_dwordx4 v[0:1], v[2:5], off
	v_lshl_add_u64 v[0:1], v[72:73], 0, s[4:5]
	s_addc_u32 s14, s65, 0
	s_lshl_b32 s4, s49, 2
	s_and_b32 s4, s4, 0x7ff00
	s_add_u32 s15, s64, s4
	v_mov_b32_e32 v2, 0
	s_addc_u32 s24, s65, 0
	s_mov_b64 s[4:5], 0
	v_mov_b32_e32 v6, v89
	v_mov_b32_e32 v3, v2
	v_readlane_b32 s53, v253, 19
	v_readlane_b32 s54, v253, 20
	v_readlane_b32 s55, v253, 21
	v_readlane_b32 s56, v253, 22
	v_readlane_b32 s57, v253, 23
	v_readlane_b32 s58, v253, 24
	v_readlane_b32 s59, v253, 25
	v_readlane_b32 s60, v253, 26
	v_readlane_b32 s61, v253, 27
	v_readlane_b32 s62, v253, 28
	v_readlane_b32 s63, v253, 29
	v_readlane_b32 s66, v253, 32
	v_readlane_b32 s67, v253, 33
	s_add_u32 s6, s15, s2
	s_addc_u32 s7, s24, s3
	v_and_b32_e32 v154, 63, v252
	v_lshlrev_b32_e32 v154, 2, v154
	v_mov_b32_e32 v156, v0
	v_mov_b32_e32 v157, v1
	global_load_dword v155, v154, s[6:7]
	s_mov_b64 s[6:7], 0x2000
	global_load_dword v158, v[156:157], off
	v_lshl_add_u64 v[156:157], v[156:157], 0, s[6:7]
	global_load_dword v159, v[156:157], off
	v_lshl_add_u64 v[156:157], v[156:157], 0, s[6:7]
	global_load_dword v160, v[156:157], off
	v_lshl_add_u64 v[156:157], v[156:157], 0, s[6:7]
	global_load_dword v161, v[156:157], off
	v_lshl_add_u64 v[156:157], v[156:157], 0, s[6:7]
	global_load_dword v162, v[156:157], off
	v_lshl_add_u64 v[156:157], v[156:157], 0, s[6:7]
	global_load_dword v163, v[156:157], off
	v_lshl_add_u64 v[156:157], v[156:157], 0, s[6:7]
	global_load_dword v164, v[156:157], off
	v_lshl_add_u64 v[156:157], v[156:157], 0, s[6:7]
	global_load_dword v165, v[156:157], off
	v_lshl_add_u64 v[156:157], v[156:157], 0, s[6:7]
	global_load_dword v166, v[156:157], off
	v_lshl_add_u64 v[156:157], v[156:157], 0, s[6:7]
	global_load_dword v167, v[156:157], off
	v_lshl_add_u64 v[156:157], v[156:157], 0, s[6:7]
	global_load_dword v168, v[156:157], off
	v_lshl_add_u64 v[156:157], v[156:157], 0, s[6:7]
	global_load_dword v174, v[156:157], off
	v_lshl_add_u64 v[156:157], v[156:157], 0, s[6:7]
	global_load_dword v175, v[156:157], off
	v_lshl_add_u64 v[156:157], v[156:157], 0, s[6:7]
	global_load_dword v176, v[156:157], off
	v_lshl_add_u64 v[156:157], v[156:157], 0, s[6:7]
	global_load_dword v177, v[156:157], off
	v_lshl_add_u64 v[156:157], v[156:157], 0, s[6:7]
	global_load_dword v178, v[156:157], off
	v_lshl_add_u64 v[156:157], v[156:157], 0, s[6:7]
	global_load_dword v179, v[156:157], off
	v_lshl_add_u64 v[156:157], v[156:157], 0, s[6:7]
	global_load_dword v180, v[156:157], off
	v_lshl_add_u64 v[156:157], v[156:157], 0, s[6:7]
	global_load_dword v181, v[156:157], off
	v_lshl_add_u64 v[156:157], v[156:157], 0, s[6:7]
	global_load_dword v182, v[156:157], off
	v_lshl_add_u64 v[156:157], v[156:157], 0, s[6:7]
	global_load_dword v183, v[156:157], off
	v_lshl_add_u64 v[156:157], v[156:157], 0, s[6:7]
	global_load_dword v184, v[156:157], off
	v_lshl_add_u64 v[156:157], v[156:157], 0, s[6:7]
	global_load_dword v185, v[156:157], off
	v_lshl_add_u64 v[156:157], v[156:157], 0, s[6:7]
	global_load_dword v186, v[156:157], off
	v_lshl_add_u64 v[156:157], v[156:157], 0, s[6:7]
	global_load_dword v187, v[156:157], off
	v_lshl_add_u64 v[156:157], v[156:157], 0, s[6:7]
	global_load_dword v188, v[156:157], off
	v_lshl_add_u64 v[156:157], v[156:157], 0, s[6:7]
	global_load_dword v189, v[156:157], off
	v_lshl_add_u64 v[156:157], v[156:157], 0, s[6:7]
	global_load_dword v190, v[156:157], off
	v_lshl_add_u64 v[156:157], v[156:157], 0, s[6:7]
	global_load_dword v191, v[156:157], off
	v_lshl_add_u64 v[156:157], v[156:157], 0, s[6:7]
	global_load_dword v192, v[156:157], off
	v_lshl_add_u64 v[156:157], v[156:157], 0, s[6:7]
	global_load_dword v193, v[156:157], off
	v_lshl_add_u64 v[156:157], v[156:157], 0, s[6:7]
	global_load_dword v194, v[156:157], off
	v_lshl_add_u64 v[156:157], v[156:157], 0, s[6:7]
	global_load_dword v195, v[156:157], off
	v_lshl_add_u64 v[156:157], v[156:157], 0, s[6:7]
	global_load_dword v196, v[156:157], off
	v_lshl_add_u64 v[156:157], v[156:157], 0, s[6:7]
	global_load_dword v197, v[156:157], off
	v_lshl_add_u64 v[156:157], v[156:157], 0, s[6:7]
	global_load_dword v198, v[156:157], off
	v_lshl_add_u64 v[156:157], v[156:157], 0, s[6:7]
	global_load_dword v199, v[156:157], off
	v_lshl_add_u64 v[156:157], v[156:157], 0, s[6:7]
	global_load_dword v200, v[156:157], off
	v_lshl_add_u64 v[156:157], v[156:157], 0, s[6:7]
	global_load_dword v201, v[156:157], off
	v_lshl_add_u64 v[156:157], v[156:157], 0, s[6:7]
	global_load_dword v202, v[156:157], off
	v_lshl_add_u64 v[156:157], v[156:157], 0, s[6:7]
	global_load_dword v203, v[156:157], off
	v_lshl_add_u64 v[156:157], v[156:157], 0, s[6:7]
	global_load_dword v204, v[156:157], off
	v_lshl_add_u64 v[156:157], v[156:157], 0, s[6:7]
	global_load_dword v205, v[156:157], off
	v_lshl_add_u64 v[156:157], v[156:157], 0, s[6:7]
	global_load_dword v206, v[156:157], off
	v_lshl_add_u64 v[156:157], v[156:157], 0, s[6:7]
	global_load_dword v207, v[156:157], off
	v_lshl_add_u64 v[156:157], v[156:157], 0, s[6:7]
	global_load_dword v208, v[156:157], off
	v_lshl_add_u64 v[156:157], v[156:157], 0, s[6:7]
	global_load_dword v209, v[156:157], off
	v_lshl_add_u64 v[156:157], v[156:157], 0, s[6:7]
	global_load_dword v210, v[156:157], off
	v_lshl_add_u64 v[156:157], v[156:157], 0, s[6:7]
	v_add_u32_e32 v25, 0x400, v6
	ds_read2_b32 v[8:9], v6 offset1:65
	ds_read2_b32 v[10:11], v6 offset0:130 offset1:195
	ds_read2_b32 v[12:13], v25 offset0:4 offset1:69
	ds_read2_b32 v[14:15], v25 offset0:134 offset1:199
	v_add_u32_e32 v24, 0x820, v6
	v_add_u32_e32 v25, 0xc20, v6
	ds_read2_b32 v[16:17], v24 offset1:65
	ds_read2_b32 v[18:19], v24 offset0:130 offset1:195
	ds_read2_b32 v[20:21], v25 offset0:4 offset1:69
	ds_read2_b32 v[22:23], v25 offset0:134 offset1:199
	s_waitcnt vmcnt(32)
; __device__ __forceinline__ unsigned f2bf(float f) { return pk2(f, 0.f) & 0xffffu; }
; __device__ __forceinline__ void p0_transpose_item(const float* W, int K, int N, bf16* WT, float* scr, int item, int lane, const float* scale, const float* cb, float* c1, float* c2) {
;     ...
;     if (c1) { float a1 = 0.f, a2 = 0.f;
;         for (int kk = 0; kk < 64; ++kk) { a1 += __uint_as_float(f2bf(scr[kk * 65 + lane]) << 16); a2 += cb[k0 + kk] * W[(size_t)(k0 + kk) * N + n0 + lane]; }
	s_waitcnt lgkmcnt(4)
	v_cvt_pk_bf16_f32 v26, v8, v169
	v_readlane_b32 vcc_lo, v155, 0
	v_lshlrev_b32_e32 v26, 16, v26
	v_mul_f32_e32 v27, vcc_lo, v158
	v_add_f32_e32 v3, v3, v26
	v_add_f32_e32 v2, v2, v27
	v_cvt_pk_bf16_f32 v28, v9, v169
	v_readlane_b32 vcc_hi, v155, 1
	v_lshlrev_b32_e32 v28, 16, v28
	v_mul_f32_e32 v29, vcc_hi, v159
	v_add_f32_e32 v3, v3, v28
	v_add_f32_e32 v2, v2, v29
	v_cvt_pk_bf16_f32 v26, v10, v169
	v_readlane_b32 vcc_lo, v155, 2
	v_lshlrev_b32_e32 v26, 16, v26
	v_mul_f32_e32 v27, vcc_lo, v160
	v_add_f32_e32 v3, v3, v26
	v_add_f32_e32 v2, v2, v27
	v_cvt_pk_bf16_f32 v28, v11, v169
	v_readlane_b32 vcc_hi, v155, 3
	v_lshlrev_b32_e32 v28, 16, v28
	v_mul_f32_e32 v29, vcc_hi, v161
	v_add_f32_e32 v3, v3, v28
	v_add_f32_e32 v2, v2, v29
	v_cvt_pk_bf16_f32 v26, v12, v169
	v_readlane_b32 vcc_lo, v155, 4
	v_lshlrev_b32_e32 v26, 16, v26
	v_mul_f32_e32 v27, vcc_lo, v162
	v_add_f32_e32 v3, v3, v26
	v_add_f32_e32 v2, v2, v27
	v_cvt_pk_bf16_f32 v28, v13, v169
	v_readlane_b32 vcc_hi, v155, 5
	v_lshlrev_b32_e32 v28, 16, v28
	v_mul_f32_e32 v29, vcc_hi, v163
	v_add_f32_e32 v3, v3, v28
	v_add_f32_e32 v2, v2, v29
	v_cvt_pk_bf16_f32 v26, v14, v169
	v_readlane_b32 vcc_lo, v155, 6
	v_lshlrev_b32_e32 v26, 16, v26
	v_mul_f32_e32 v27, vcc_lo, v164
	v_add_f32_e32 v3, v3, v26
	v_add_f32_e32 v2, v2, v27
	v_cvt_pk_bf16_f32 v28, v15, v169
	v_readlane_b32 vcc_hi, v155, 7
	v_lshlrev_b32_e32 v28, 16, v28
	v_mul_f32_e32 v29, vcc_hi, v165
	v_add_f32_e32 v3, v3, v28
	v_add_f32_e32 v2, v2, v29
	v_add_u32_e32 v24, 0x1040, v6
	v_add_u32_e32 v25, 0x1440, v6
	ds_read2_b32 v[8:9], v24 offset1:65
	ds_read2_b32 v[10:11], v24 offset0:130 offset1:195
	ds_read2_b32 v[12:13], v25 offset0:4 offset1:69
	ds_read2_b32 v[14:15], v25 offset0:134 offset1:199
	s_waitcnt lgkmcnt(4)
	v_cvt_pk_bf16_f32 v26, v16, v169
	v_readlane_b32 vcc_lo, v155, 8
	v_lshlrev_b32_e32 v26, 16, v26
	v_mul_f32_e32 v27, vcc_lo, v166
	v_add_f32_e32 v3, v3, v26
	v_add_f32_e32 v2, v2, v27
	v_cvt_pk_bf16_f32 v28, v17, v169
	v_readlane_b32 vcc_hi, v155, 9
	v_lshlrev_b32_e32 v28, 16, v28
	v_mul_f32_e32 v29, vcc_hi, v167
	v_add_f32_e32 v3, v3, v28
	v_add_f32_e32 v2, v2, v29
	v_cvt_pk_bf16_f32 v26, v18, v169
	v_readlane_b32 vcc_lo, v155, 10
	v_lshlrev_b32_e32 v26, 16, v26
	v_mul_f32_e32 v27, vcc_lo, v168
	v_add_f32_e32 v3, v3, v26
	v_add_f32_e32 v2, v2, v27
	v_cvt_pk_bf16_f32 v28, v19, v169
	v_readlane_b32 vcc_hi, v155, 11
	v_lshlrev_b32_e32 v28, 16, v28
	v_mul_f32_e32 v29, vcc_hi, v174
	v_add_f32_e32 v3, v3, v28
	v_add_f32_e32 v2, v2, v29
	v_cvt_pk_bf16_f32 v26, v20, v169
	v_readlane_b32 vcc_lo, v155, 12
	v_lshlrev_b32_e32 v26, 16, v26
	v_mul_f32_e32 v27, vcc_lo, v175
	v_add_f32_e32 v3, v3, v26
	v_add_f32_e32 v2, v2, v27
	v_cvt_pk_bf16_f32 v28, v21, v169
	v_readlane_b32 vcc_hi, v155, 13
	v_lshlrev_b32_e32 v28, 16, v28
	v_mul_f32_e32 v29, vcc_hi, v176
	v_add_f32_e32 v3, v3, v28
	v_add_f32_e32 v2, v2, v29
	v_cvt_pk_bf16_f32 v26, v22, v169
	v_readlane_b32 vcc_lo, v155, 14
	v_lshlrev_b32_e32 v26, 16, v26
	v_mul_f32_e32 v27, vcc_lo, v177
	v_add_f32_e32 v3, v3, v26
	v_add_f32_e32 v2, v2, v27
	v_cvt_pk_bf16_f32 v28, v23, v169
	v_readlane_b32 vcc_hi, v155, 15
	v_lshlrev_b32_e32 v28, 16, v28
	v_mul_f32_e32 v29, vcc_hi, v178
	v_add_f32_e32 v3, v3, v28
	v_add_f32_e32 v2, v2, v29
	global_load_dword v211, v[156:157], off
	v_lshl_add_u64 v[156:157], v[156:157], 0, s[6:7]
	global_load_dword v212, v[156:157], off
	v_lshl_add_u64 v[156:157], v[156:157], 0, s[6:7]
	global_load_dword v213, v[156:157], off
	v_lshl_add_u64 v[156:157], v[156:157], 0, s[6:7]
	global_load_dword v224, v[156:157], off
	v_lshl_add_u64 v[156:157], v[156:157], 0, s[6:7]
	global_load_dword v225, v[156:157], off
	v_lshl_add_u64 v[156:157], v[156:157], 0, s[6:7]
	global_load_dword v226, v[156:157], off
	v_lshl_add_u64 v[156:157], v[156:157], 0, s[6:7]
	global_load_dword v227, v[156:157], off
	v_lshl_add_u64 v[156:157], v[156:157], 0, s[6:7]
	global_load_dword v228, v[156:157], off
	v_lshl_add_u64 v[156:157], v[156:157], 0, s[6:7]
	global_load_dword v229, v[156:157], off
	v_lshl_add_u64 v[156:157], v[156:157], 0, s[6:7]
	global_load_dword v230, v[156:157], off
	v_lshl_add_u64 v[156:157], v[156:157], 0, s[6:7]
	global_load_dword v231, v[156:157], off
	v_lshl_add_u64 v[156:157], v[156:157], 0, s[6:7]
	global_load_dword v232, v[156:157], off
	v_lshl_add_u64 v[156:157], v[156:157], 0, s[6:7]
	global_load_dword v233, v[156:157], off
	v_lshl_add_u64 v[156:157], v[156:157], 0, s[6:7]
	global_load_dword v234, v[156:157], off
	v_lshl_add_u64 v[156:157], v[156:157], 0, s[6:7]
	global_load_dword v235, v[156:157], off
	v_lshl_add_u64 v[156:157], v[156:157], 0, s[6:7]
	global_load_dword v236, v[156:157], off
	v_lshl_add_u64 v[156:157], v[156:157], 0, s[6:7]
	v_add_u32_e32 v24, 0x1860, v6
	v_add_u32_e32 v25, 0x1c60, v6
	ds_read2_b32 v[16:17], v24 offset1:65
	ds_read2_b32 v[18:19], v24 offset0:130 offset1:195
	ds_read2_b32 v[20:21], v25 offset0:4 offset1:69
	ds_read2_b32 v[22:23], v25 offset0:134 offset1:199
	s_waitcnt vmcnt(32)
	s_waitcnt lgkmcnt(4)
; __device__ __forceinline__ unsigned f2bf(float f) { return pk2(f, 0.f) & 0xffffu; }
; __device__ __forceinline__ void p0_transpose_item(const float* W, int K, int N, bf16* WT, float* scr, int item, int lane, const float* scale, const float* cb, float* c1, float* c2) {
;     ...
;     if (c1) { float a1 = 0.f, a2 = 0.f;
;         for (int kk = 0; kk < 64; ++kk) { a1 += __uint_as_float(f2bf(scr[kk * 65 + lane]) << 16); a2 += cb[k0 + kk] * W[(size_t)(k0 + kk) * N + n0 + lane]; }
	v_cvt_pk_bf16_f32 v26, v8, v169
	v_readlane_b32 vcc_lo, v155, 16
	v_lshlrev_b32_e32 v26, 16, v26
	v_mul_f32_e32 v27, vcc_lo, v179
	v_add_f32_e32 v3, v3, v26
	v_add_f32_e32 v2, v2, v27
	v_cvt_pk_bf16_f32 v28, v9, v169
	v_readlane_b32 vcc_hi, v155, 17
	v_lshlrev_b32_e32 v28, 16, v28
	v_mul_f32_e32 v29, vcc_hi, v180
	v_add_f32_e32 v3, v3, v28
	v_add_f32_e32 v2, v2, v29
	v_cvt_pk_bf16_f32 v26, v10, v169
	v_readlane_b32 vcc_lo, v155, 18
	v_lshlrev_b32_e32 v26, 16, v26
	v_mul_f32_e32 v27, vcc_lo, v181
	v_add_f32_e32 v3, v3, v26
	v_add_f32_e32 v2, v2, v27
	v_cvt_pk_bf16_f32 v28, v11, v169
	v_readlane_b32 vcc_hi, v155, 19
	v_lshlrev_b32_e32 v28, 16, v28
	v_mul_f32_e32 v29, vcc_hi, v182
	v_add_f32_e32 v3, v3, v28
	v_add_f32_e32 v2, v2, v29
	v_cvt_pk_bf16_f32 v26, v12, v169
	v_readlane_b32 vcc_lo, v155, 20
	v_lshlrev_b32_e32 v26, 16, v26
	v_mul_f32_e32 v27, vcc_lo, v183
	v_add_f32_e32 v3, v3, v26
	v_add_f32_e32 v2, v2, v27
	v_cvt_pk_bf16_f32 v28, v13, v169
	v_readlane_b32 vcc_hi, v155, 21
	v_lshlrev_b32_e32 v28, 16, v28
	v_mul_f32_e32 v29, vcc_hi, v184
	v_add_f32_e32 v3, v3, v28
	v_add_f32_e32 v2, v2, v29
	v_cvt_pk_bf16_f32 v26, v14, v169
	v_readlane_b32 vcc_lo, v155, 22
	v_lshlrev_b32_e32 v26, 16, v26
	v_mul_f32_e32 v27, vcc_lo, v185
	v_add_f32_e32 v3, v3, v26
	v_add_f32_e32 v2, v2, v27
	v_cvt_pk_bf16_f32 v28, v15, v169
	v_readlane_b32 vcc_hi, v155, 23
	v_lshlrev_b32_e32 v28, 16, v28
	v_mul_f32_e32 v29, vcc_hi, v186
	v_add_f32_e32 v3, v3, v28
	v_add_f32_e32 v2, v2, v29
	v_add_u32_e32 v24, 0x2080, v6
	v_add_u32_e32 v25, 0x2480, v6
	ds_read2_b32 v[8:9], v24 offset1:65
	ds_read2_b32 v[10:11], v24 offset0:130 offset1:195
	ds_read2_b32 v[12:13], v25 offset0:4 offset1:69
	ds_read2_b32 v[14:15], v25 offset0:134 offset1:199
	s_waitcnt lgkmcnt(4)
	v_cvt_pk_bf16_f32 v26, v16, v169
	v_readlane_b32 vcc_lo, v155, 24
	v_lshlrev_b32_e32 v26, 16, v26
	v_mul_f32_e32 v27, vcc_lo, v187
	v_add_f32_e32 v3, v3, v26
	v_add_f32_e32 v2, v2, v27
	v_cvt_pk_bf16_f32 v28, v17, v169
	v_readlane_b32 vcc_hi, v155, 25
	v_lshlrev_b32_e32 v28, 16, v28
	v_mul_f32_e32 v29, vcc_hi, v188
	v_add_f32_e32 v3, v3, v28
	v_add_f32_e32 v2, v2, v29
	v_cvt_pk_bf16_f32 v26, v18, v169
	v_readlane_b32 vcc_lo, v155, 26
	v_lshlrev_b32_e32 v26, 16, v26
	v_mul_f32_e32 v27, vcc_lo, v189
	v_add_f32_e32 v3, v3, v26
	v_add_f32_e32 v2, v2, v27
	v_cvt_pk_bf16_f32 v28, v19, v169
	v_readlane_b32 vcc_hi, v155, 27
	v_lshlrev_b32_e32 v28, 16, v28
	v_mul_f32_e32 v29, vcc_hi, v190
	v_add_f32_e32 v3, v3, v28
	v_add_f32_e32 v2, v2, v29
	v_cvt_pk_bf16_f32 v26, v20, v169
	v_readlane_b32 vcc_lo, v155, 28
	v_lshlrev_b32_e32 v26, 16, v26
	v_mul_f32_e32 v27, vcc_lo, v191
	v_add_f32_e32 v3, v3, v26
	v_add_f32_e32 v2, v2, v27
	v_cvt_pk_bf16_f32 v28, v21, v169
	v_readlane_b32 vcc_hi, v155, 29
	v_lshlrev_b32_e32 v28, 16, v28
	v_mul_f32_e32 v29, vcc_hi, v192
	v_add_f32_e32 v3, v3, v28
	v_add_f32_e32 v2, v2, v29
	v_cvt_pk_bf16_f32 v26, v22, v169
	v_readlane_b32 vcc_lo, v155, 30
	v_lshlrev_b32_e32 v26, 16, v26
	v_mul_f32_e32 v27, vcc_lo, v193
	v_add_f32_e32 v3, v3, v26
	v_add_f32_e32 v2, v2, v27
	v_cvt_pk_bf16_f32 v28, v23, v169
	v_readlane_b32 vcc_hi, v155, 31
	v_lshlrev_b32_e32 v28, 16, v28
	v_mul_f32_e32 v29, vcc_hi, v194
	v_add_f32_e32 v3, v3, v28
	v_add_f32_e32 v2, v2, v29
	v_add_u32_e32 v24, 0x28a0, v6
	v_add_u32_e32 v25, 0x2ca0, v6
	ds_read2_b32 v[16:17], v24 offset1:65
	ds_read2_b32 v[18:19], v24 offset0:130 offset1:195
	ds_read2_b32 v[20:21], v25 offset0:4 offset1:69
	ds_read2_b32 v[22:23], v25 offset0:134 offset1:199
	s_waitcnt vmcnt(16)
	s_waitcnt lgkmcnt(4)
	v_cvt_pk_bf16_f32 v26, v8, v169
	v_readlane_b32 vcc_lo, v155, 32
	v_lshlrev_b32_e32 v26, 16, v26
	v_mul_f32_e32 v27, vcc_lo, v195
	v_add_f32_e32 v3, v3, v26
	v_add_f32_e32 v2, v2, v27
	v_cvt_pk_bf16_f32 v28, v9, v169
	v_readlane_b32 vcc_hi, v155, 33
	v_lshlrev_b32_e32 v28, 16, v28
	v_mul_f32_e32 v29, vcc_hi, v196
	v_add_f32_e32 v3, v3, v28
	v_add_f32_e32 v2, v2, v29
	v_cvt_pk_bf16_f32 v26, v10, v169
	v_readlane_b32 vcc_lo, v155, 34
	v_lshlrev_b32_e32 v26, 16, v26
	v_mul_f32_e32 v27, vcc_lo, v197
	v_add_f32_e32 v3, v3, v26
	v_add_f32_e32 v2, v2, v27
	v_cvt_pk_bf16_f32 v28, v11, v169
	v_readlane_b32 vcc_hi, v155, 35
	v_lshlrev_b32_e32 v28, 16, v28
	v_mul_f32_e32 v29, vcc_hi, v198
	v_add_f32_e32 v3, v3, v28
	v_add_f32_e32 v2, v2, v29
	v_cvt_pk_bf16_f32 v26, v12, v169
	v_readlane_b32 vcc_lo, v155, 36
	v_lshlrev_b32_e32 v26, 16, v26
	v_mul_f32_e32 v27, vcc_lo, v199
	v_add_f32_e32 v3, v3, v26
	v_add_f32_e32 v2, v2, v27
	v_cvt_pk_bf16_f32 v28, v13, v169
	v_readlane_b32 vcc_hi, v155, 37
	v_lshlrev_b32_e32 v28, 16, v28
	v_mul_f32_e32 v29, vcc_hi, v200
	v_add_f32_e32 v3, v3, v28
	v_add_f32_e32 v2, v2, v29
	v_cvt_pk_bf16_f32 v26, v14, v169
	v_readlane_b32 vcc_lo, v155, 38
	v_lshlrev_b32_e32 v26, 16, v26
	v_mul_f32_e32 v27, vcc_lo, v201
	v_add_f32_e32 v3, v3, v26
	v_add_f32_e32 v2, v2, v27
	v_cvt_pk_bf16_f32 v28, v15, v169
	v_readlane_b32 vcc_hi, v155, 39
	v_lshlrev_b32_e32 v28, 16, v28
	v_mul_f32_e32 v29, vcc_hi, v202
	v_add_f32_e32 v3, v3, v28
	v_add_f32_e32 v2, v2, v29
	v_add_u32_e32 v24, 0x30c0, v6
	v_add_u32_e32 v25, 0x34c0, v6
	ds_read2_b32 v[8:9], v24 offset1:65
	ds_read2_b32 v[10:11], v24 offset0:130 offset1:195
	ds_read2_b32 v[12:13], v25 offset0:4 offset1:69
	ds_read2_b32 v[14:15], v25 offset0:134 offset1:199
	s_waitcnt lgkmcnt(4)
; __device__ __forceinline__ unsigned f2bf(float f) { return pk2(f, 0.f) & 0xffffu; }
; __device__ __forceinline__ void p0_transpose_item(const float* W, int K, int N, bf16* WT, float* scr, int item, int lane, const float* scale, const float* cb, float* c1, float* c2) {
;     ...
;     if (c1) { float a1 = 0.f, a2 = 0.f;
;         for (int kk = 0; kk < 64; ++kk) { a1 += __uint_as_float(f2bf(scr[kk * 65 + lane]) << 16); a2 += cb[k0 + kk] * W[(size_t)(k0 + kk) * N + n0 + lane]; }
;         atomicAdd(c1 + n0 + lane, a1); atomicAdd(c2 + n0 + lane, a2); }
	v_cvt_pk_bf16_f32 v26, v16, v169
	v_readlane_b32 vcc_lo, v155, 40
	v_lshlrev_b32_e32 v26, 16, v26
	v_mul_f32_e32 v27, vcc_lo, v203
	v_add_f32_e32 v3, v3, v26
	v_add_f32_e32 v2, v2, v27
	v_cvt_pk_bf16_f32 v28, v17, v169
	v_readlane_b32 vcc_hi, v155, 41
	v_lshlrev_b32_e32 v28, 16, v28
	v_mul_f32_e32 v29, vcc_hi, v204
	v_add_f32_e32 v3, v3, v28
	v_add_f32_e32 v2, v2, v29
	v_cvt_pk_bf16_f32 v26, v18, v169
	v_readlane_b32 vcc_lo, v155, 42
	v_lshlrev_b32_e32 v26, 16, v26
	v_mul_f32_e32 v27, vcc_lo, v205
	v_add_f32_e32 v3, v3, v26
	v_add_f32_e32 v2, v2, v27
	v_cvt_pk_bf16_f32 v28, v19, v169
	v_readlane_b32 vcc_hi, v155, 43
	v_lshlrev_b32_e32 v28, 16, v28
	v_mul_f32_e32 v29, vcc_hi, v206
	v_add_f32_e32 v3, v3, v28
	v_add_f32_e32 v2, v2, v29
	v_cvt_pk_bf16_f32 v26, v20, v169
	v_readlane_b32 vcc_lo, v155, 44
	v_lshlrev_b32_e32 v26, 16, v26
	v_mul_f32_e32 v27, vcc_lo, v207
	v_add_f32_e32 v3, v3, v26
	v_add_f32_e32 v2, v2, v27
	v_cvt_pk_bf16_f32 v28, v21, v169
	v_readlane_b32 vcc_hi, v155, 45
	v_lshlrev_b32_e32 v28, 16, v28
	v_mul_f32_e32 v29, vcc_hi, v208
	v_add_f32_e32 v3, v3, v28
	v_add_f32_e32 v2, v2, v29
	v_cvt_pk_bf16_f32 v26, v22, v169
	v_readlane_b32 vcc_lo, v155, 46
	v_lshlrev_b32_e32 v26, 16, v26
	v_mul_f32_e32 v27, vcc_lo, v209
	v_add_f32_e32 v3, v3, v26
	v_add_f32_e32 v2, v2, v27
	v_cvt_pk_bf16_f32 v28, v23, v169
	v_readlane_b32 vcc_hi, v155, 47
	v_lshlrev_b32_e32 v28, 16, v28
	v_mul_f32_e32 v29, vcc_hi, v210
	v_add_f32_e32 v3, v3, v28
	v_add_f32_e32 v2, v2, v29
	v_add_u32_e32 v24, 0x38e0, v6
	v_add_u32_e32 v25, 0x3ce0, v6
	ds_read2_b32 v[16:17], v24 offset1:65
	ds_read2_b32 v[18:19], v24 offset0:130 offset1:195
	ds_read2_b32 v[20:21], v25 offset0:4 offset1:69
	ds_read2_b32 v[22:23], v25 offset0:134 offset1:199
	s_waitcnt vmcnt(0)
	s_waitcnt lgkmcnt(4)
	v_cvt_pk_bf16_f32 v26, v8, v169
	v_readlane_b32 vcc_lo, v155, 48
	v_lshlrev_b32_e32 v26, 16, v26
	v_mul_f32_e32 v27, vcc_lo, v211
	v_add_f32_e32 v3, v3, v26
	v_add_f32_e32 v2, v2, v27
	v_cvt_pk_bf16_f32 v28, v9, v169
	v_readlane_b32 vcc_hi, v155, 49
	v_lshlrev_b32_e32 v28, 16, v28
	v_mul_f32_e32 v29, vcc_hi, v212
	v_add_f32_e32 v3, v3, v28
	v_add_f32_e32 v2, v2, v29
	v_cvt_pk_bf16_f32 v26, v10, v169
	v_readlane_b32 vcc_lo, v155, 50
	v_lshlrev_b32_e32 v26, 16, v26
	v_mul_f32_e32 v27, vcc_lo, v213
	v_add_f32_e32 v3, v3, v26
	v_add_f32_e32 v2, v2, v27
	v_cvt_pk_bf16_f32 v28, v11, v169
	v_readlane_b32 vcc_hi, v155, 51
	v_lshlrev_b32_e32 v28, 16, v28
	v_mul_f32_e32 v29, vcc_hi, v224
	v_add_f32_e32 v3, v3, v28
	v_add_f32_e32 v2, v2, v29
	v_cvt_pk_bf16_f32 v26, v12, v169
	v_readlane_b32 vcc_lo, v155, 52
	v_lshlrev_b32_e32 v26, 16, v26
	v_mul_f32_e32 v27, vcc_lo, v225
	v_add_f32_e32 v3, v3, v26
	v_add_f32_e32 v2, v2, v27
	v_cvt_pk_bf16_f32 v28, v13, v169
	v_readlane_b32 vcc_hi, v155, 53
	v_lshlrev_b32_e32 v28, 16, v28
	v_mul_f32_e32 v29, vcc_hi, v226
	v_add_f32_e32 v3, v3, v28
	v_add_f32_e32 v2, v2, v29
	v_cvt_pk_bf16_f32 v26, v14, v169
	v_readlane_b32 vcc_lo, v155, 54
	v_lshlrev_b32_e32 v26, 16, v26
	v_mul_f32_e32 v27, vcc_lo, v227
	v_add_f32_e32 v3, v3, v26
	v_add_f32_e32 v2, v2, v27
	v_cvt_pk_bf16_f32 v28, v15, v169
	v_readlane_b32 vcc_hi, v155, 55
	v_lshlrev_b32_e32 v28, 16, v28
	v_mul_f32_e32 v29, vcc_hi, v228
	v_add_f32_e32 v3, v3, v28
	v_add_f32_e32 v2, v2, v29
	s_waitcnt lgkmcnt(0)
	v_cvt_pk_bf16_f32 v26, v16, v169
	v_readlane_b32 vcc_lo, v155, 56
	v_lshlrev_b32_e32 v26, 16, v26
	v_mul_f32_e32 v27, vcc_lo, v229
	v_add_f32_e32 v3, v3, v26
	v_add_f32_e32 v2, v2, v27
	v_cvt_pk_bf16_f32 v28, v17, v169
	v_readlane_b32 vcc_hi, v155, 57
	v_lshlrev_b32_e32 v28, 16, v28
	v_mul_f32_e32 v29, vcc_hi, v230
	v_add_f32_e32 v3, v3, v28
	v_add_f32_e32 v2, v2, v29
	v_cvt_pk_bf16_f32 v26, v18, v169
	v_readlane_b32 vcc_lo, v155, 58
	v_lshlrev_b32_e32 v26, 16, v26
	v_mul_f32_e32 v27, vcc_lo, v231
	v_add_f32_e32 v3, v3, v26
	v_add_f32_e32 v2, v2, v27
	v_cvt_pk_bf16_f32 v28, v19, v169
	v_readlane_b32 vcc_hi, v155, 59
	v_lshlrev_b32_e32 v28, 16, v28
	v_mul_f32_e32 v29, vcc_hi, v232
	v_add_f32_e32 v3, v3, v28
	v_add_f32_e32 v2, v2, v29
	v_cvt_pk_bf16_f32 v26, v20, v169
	v_readlane_b32 vcc_lo, v155, 60
	v_lshlrev_b32_e32 v26, 16, v26
	v_mul_f32_e32 v27, vcc_lo, v233
	v_add_f32_e32 v3, v3, v26
	v_add_f32_e32 v2, v2, v27
	v_cvt_pk_bf16_f32 v28, v21, v169
	v_readlane_b32 vcc_hi, v155, 61
	v_lshlrev_b32_e32 v28, 16, v28
	v_mul_f32_e32 v29, vcc_hi, v234
	v_add_f32_e32 v3, v3, v28
	v_add_f32_e32 v2, v2, v29
	v_cvt_pk_bf16_f32 v26, v22, v169
	v_readlane_b32 vcc_lo, v155, 62
	v_lshlrev_b32_e32 v26, 16, v26
	v_mul_f32_e32 v27, vcc_lo, v235
	v_add_f32_e32 v3, v3, v26
	v_add_f32_e32 v2, v2, v27
	v_cvt_pk_bf16_f32 v28, v23, v169
	v_readlane_b32 vcc_hi, v155, 63
	v_lshlrev_b32_e32 v28, 16, v28
	v_mul_f32_e32 v29, vcc_hi, v236
	v_add_f32_e32 v3, v3, v28
	v_add_f32_e32 v2, v2, v29
	s_add_u32 s1, s43, s2
	s_addc_u32 s4, s44, s3
	s_add_u32 s5, s45, s2
	s_addc_u32 s6, s46, s3
	s_add_u32 s2, s1, s48
	s_addc_u32 s3, s4, 0
	v_mov_b32_e32 v75, v169
	v_lshl_add_u64 v[0:1], s[2:3], 0, v[74:75]
	s_add_u32 s2, s5, s48
	s_addc_u32 s3, s6, 0
	global_atomic_add_f32 v[0:1], v3, off
	v_lshl_add_u64 v[0:1], s[2:3], 0, v[74:75]
	global_atomic_add_f32 v[0:1], v2, off
	s_waitcnt lgkmcnt(0)

; __global__ void __launch_bounds__(512, 2) mk_fwd(Args args) {
	.amdhsa_kernel _Z6mk_fwd4Args
		.amdhsa_group_segment_fixed_size 0
		.amdhsa_private_segment_fixed_size 0
		.amdhsa_kernarg_size 416
		.amdhsa_user_sgpr_count 2
		.amdhsa_user_sgpr_dispatch_ptr 0
		.amdhsa_user_sgpr_queue_ptr 0
		.amdhsa_user_sgpr_kernarg_segment_ptr 1
		.amdhsa_user_sgpr_dispatch_id 0
		.amdhsa_user_sgpr_kernarg_preload_length 0
		.amdhsa_user_sgpr_kernarg_preload_offset 0
		.amdhsa_user_sgpr_private_segment_size 0
		.amdhsa_uses_dynamic_stack 0
		.amdhsa_enable_private_segment 0
		.amdhsa_system_sgpr_workgroup_id_x 1
		.amdhsa_system_sgpr_workgroup_id_y 0
		.amdhsa_system_sgpr_workgroup_id_z 0
		.amdhsa_system_sgpr_workgroup_info 0
		.amdhsa_system_vgpr_workitem_id 2
		.amdhsa_next_free_vgpr 256
		.amdhsa_next_free_sgpr 102
		.amdhsa_accum_offset 256
		.amdhsa_reserve_vcc 1
		.amdhsa_float_round_mode_32 0
		.amdhsa_float_round_mode_16_64 0
		.amdhsa_float_denorm_mode_32 3
		.amdhsa_float_denorm_mode_16_64 3
		.amdhsa_dx10_clamp 1
		.amdhsa_ieee_mode 1
		.amdhsa_fp16_overflow 0
		.amdhsa_tg_split 0
		.amdhsa_exception_fp_ieee_invalid_op 0
		.amdhsa_exception_fp_denorm_src 0
		.amdhsa_exception_fp_ieee_div_zero 0
		.amdhsa_exception_fp_ieee_overflow 0
		.amdhsa_exception_fp_ieee_underflow 0
		.amdhsa_exception_fp_ieee_inexact 0
		.amdhsa_exception_int_div_zero 0
	.end_amdhsa_kernel

; __global__ void __launch_bounds__(512, 2) mk_fwd(Args args) {
amdhsa.kernels:
  - .agpr_count:     0
    .args:
      - .offset:         0
        .size:           160
        .value_kind:     by_value
      - .offset:         160
        .size:           4
        .value_kind:     hidden_block_count_x
      - .offset:         164
        .size:           4
        .value_kind:     hidden_block_count_y
      - .offset:         168
        .size:           4
        .value_kind:     hidden_block_count_z
      - .offset:         172
        .size:           2
        .value_kind:     hidden_group_size_x
      - .offset:         174
        .size:           2
        .value_kind:     hidden_group_size_y
      - .offset:         176
        .size:           2
        .value_kind:     hidden_group_size_z
      - .offset:         178
        .size:           2
        .value_kind:     hidden_remainder_x
      - .offset:         180
        .size:           2
        .value_kind:     hidden_remainder_y
      - .offset:         182
        .size:           2
        .value_kind:     hidden_remainder_z
      - .offset:         200
        .size:           8
        .value_kind:     hidden_global_offset_x
      - .offset:         208
        .size:           8
        .value_kind:     hidden_global_offset_y
      - .offset:         216
        .size:           8
        .value_kind:     hidden_global_offset_z
      - .offset:         224
        .size:           2
        .value_kind:     hidden_grid_dims
      - .offset:         248
        .size:           8
        .value_kind:     hidden_multigrid_sync_arg
      - .offset:         280
        .size:           4
        .value_kind:     hidden_dynamic_lds_size
    .group_segment_fixed_size: 0
    .kernarg_segment_align: 8
    .kernarg_segment_size: 416
    .language:       OpenCL C
    .language_version:
      - 2
      - 0
    .max_flat_workgroup_size: 512
    .name:           _Z6mk_fwd4Args
    .private_segment_fixed_size: 0
    .sgpr_count:     108
    .sgpr_spill_count: 202
    .symbol:         _Z6mk_fwd4Args.kd
    .uniform_work_group_size: 1
    .uses_dynamic_stack: false
    .vgpr_count:     256
    .vgpr_spill_count: 0
    .wavefront_size: 64
